# scan: loader/consumer LDS-DMA, per-image hand-off, dv-half partners on one XCD; prep step-1 loads reordered with counted waits
# speedup vs baseline: 1.0047x; 1.0047x over previous
; #define PG8_LAS __attribute__((address_space(3)))
; __device__ __forceinline__ void phase_scan(const Args& a, PG8_LAS unsigned char* lds, int sblk) {
;     const int tid = threadIdx.x, lane = tid & 63, wave = tid >> 6, q = lane >> 4, r = lane & 15;
;     const int bh = sblk >> 1, dvh = sblk & 1, b = bh >> 2, h = bh & 3;
;     bf16_t* of = (bf16_t*)(a.ws + WS_OF2); const float* glast = (const float*)(a.ws + WS_GL);
;     constexpr int L_W = 0, L_QG = 17408, L_KD = 34816, L_UT = 53248, L_AQ = 71680;
;     f32x4 S[8];
; #pragma unroll
;     for (int m = 0; m < 8; ++m) S[m] = (f32x4){0.f, 0.f, 0.f, 0.f};
;     u32x4 pre[9];
;     { const unsigned char* src = a.ws + WS_PREP + (size_t)((b * 32 + 0) * 4 + h) * PREP_ITEM;
; #pragma unroll
;       for (int i = 0; i < 9; ++i) pre[i] = __builtin_nontemporal_load((const u32x4*)(src + (size_t)(tid + 512 * i) * 16)); }
.LBB0_523:
	s_andn2_b64 vcc, exec, s[0:1]
	s_cbranch_vccnz .LBB0_531
	v_readlane_b32 s0, v253, 17
	s_bitcmp0_b32 s0, 4
	s_mov_b32 s5, 0
	s_cbranch_scc1 .LBB0_531
	s_lshr_b32 s52, s82, 4
	s_lshl_b32 s52, s52, 4
	s_and_b32 s53, s82, 7
	s_lshl_b32 s53, s53, 1
	s_or_b32 s52, s52, s53
	s_bfe_u32 s53, s82, 0x10003
	s_or_b32 s52, s52, s53
	s_lshr_b32 s4, s52, 3
	s_bfe_u32 s8, s52, 0x20001
	s_and_b32 s30, s52, 1
	s_add_u32 s12, s16, 0x16000000
	s_addc_u32 s13, s17, 0
	s_lshl_b32 s0, s4, 7
	s_or_b32 s20, s0, s8
	s_mul_i32 s0, s20, 0x12000
	s_add_u32 s88, s12, s0
	s_addc_u32 s89, s13, 0
	v_mov_b32_e32 v95, 0
	s_waitcnt vmcnt(0)
	v_readfirstlane_b32 s56, v152
	s_mov_b32 s57, 0
	s_mov_b32 s86, 0
	s_lshr_b32 s56, s56, 6
	s_cmp_lt_u32 s56, 4
	s_cbranch_scc1 .Lsc_consumer
	s_cmp_lt_u32 s56, 6
	s_mov_b32 s69, 0x1c72
	s_cselect_b32 s69, 0xf10, s69
	s_cselect_b32 s70, 17, 9
	s_cselect_b32 s71, 15, 7
	s_movk_i32 s72, 0x80
	s_cselect_b32 s72, 0x100, s72
	s_mov_b32 s75, 0
	s_cmp_eq_u32 s56, 4
	s_cbranch_scc1 .Lsc_ld_w4
	s_cmp_eq_u32 s56, 5
	s_cbranch_scc1 .Lsc_ld_w5
	s_cmp_eq_u32 s56, 6
	s_cbranch_scc1 .Lsc_ld_w6
	s_mov_b32 s73, 0x10000
	s_lshl_b32 s74, s30, 13
	s_add_i32 s74, s74, 0xc000
	s_mov_b32 s75, 0xfffffdc0
	s_mov_b32 s60, 71680
	s_mov_b32 s62, 217344
	s_mul_i32 s61, s30, 0x2400
	s_add_i32 s61, s61, 44032
	s_xor_b32 s63, s61, 106496
	s_branch .Lsc_ld_tab

; #define PG8_LAS __attribute__((address_space(3)))
; __device__ __forceinline__ void phase_scan(const Args& a, PG8_LAS unsigned char* lds, int sblk) {
;     ...
;     f32x4 S[8];
; #pragma unroll
;     for (int m = 0; m < 8; ++m) S[m] = (f32x4){0.f, 0.f, 0.f, 0.f};
;     u32x4 pre[9];
;     { const unsigned char* src = a.ws + WS_PREP + (size_t)((b * 32 + 0) * 4 + h) * PREP_ITEM;
; #pragma unroll
;       for (int i = 0; i < 9; ++i) pre[i] = __builtin_nontemporal_load((const u32x4*)(src + (size_t)(tid + 512 * i) * 16)); }
;     for (int n = 0; n < 32; ++n) {
; #pragma unroll
;         for (int i = 0; i < 9; ++i) { const int p = tid + 512 * i; int off;
;             if (i < 2) off = L_W + (p >> 4) * 272 + (p & 15) * 16;
;             else if (i < 4) { const int pp = p - 1024; off = L_QG + (pp >> 4) * 272 + (pp & 15) * 16; }
;             else if (i < 6) { const int pp = p - 2048; off = L_KD + (pp >> 3) * 144 + (pp & 7) * 16; }
;             else if (i < 8) { const int pp = p - 3072; off = L_UT + (pp >> 3) * 144 + (pp & 7) * 16; }
;             else { const int pp = p - 4096; off = L_AQ + (pp >> 3) * 144 + (pp & 7) * 16; }
;             *(PG8_LAS u32x4*)(lds + off) = pre[i]; }
;         __syncthreads();
;         if (n + 1 < 32) { const unsigned char* src = a.ws + WS_PREP + (size_t)((b * 32 + n + 1) * 4 + h) * PREP_ITEM;
; #pragma unroll
;             for (int i = 0; i < 9; ++i) pre[i] = __builtin_nontemporal_load((const u32x4*)(src + (size_t)(tid + 512 * i) * 16)); }
;         if (wave < 4) {
;             __builtin_amdgcn_s_setprio(2);
;             const int dv0 = dvh * 64 + wave * 16; const float gl = glast[(b * 32 + n) * 4 + h]; const size_t row0 = (size_t)b * 2048 + n * 64;
.Lsc_consumer:
	s_add_u32 s84, s16, 0x1b00000
	s_addc_u32 s85, s17, 0
	s_lshl_b32 s0, s20, 2
	s_add_u32 s84, s84, s0
	s_addc_u32 s85, s85, 0
	v_and_b32_e32 v155, 31, v152
	v_lshlrev_b32_e32 v155, 4, v155
	global_load_dword v154, v155, s[84:85]
	v_lshrrev_b32_e32 v37, 2, v152
	s_lshl_b32 s9, s52, 6
	v_and_b32_e32 v37, 48, v37
	v_and_b32_e32 v39, 15, v152
	v_and_or_b32 v37, s9, 64, v37
	v_or_b32_e32 v42, v37, v39
	s_movk_i32 s9, 0x90
	v_bfe_u32 v36, v152, 4, 2
	v_mad_u32_u24 v42, v42, s9, 0
	s_add_i32 s9, 0, 0x11800
	s_lshl_b32 s8, s8, 8
	v_lshlrev_b32_e32 v44, 4, v36
	s_add_u32 s8, s16, s8
	v_add_u32_e32 v107, 0, v44
	v_add_u32_e32 v44, s9, v44
	s_addc_u32 s9, s17, 0
	v_lshlrev_b32_e32 v94, 1, v37
	v_lshlrev_b32_e32 v43, 3, v36
	v_lshlrev_b32_e32 v45, 2, v36
	v_lshl_add_u64 v[36:37], s[8:9], 0, v[94:95]
	v_lshlrev_b32_e32 v94, 1, v39
	v_lshl_add_u64 v[36:37], v[36:37], 0, v[94:95]
	s_mov_b64 s[8:9], 0x10000000
	v_lshl_add_u64 v[104:105], v[36:37], 0, s[8:9]
	v_mul_u32_u24_e32 v52, 0x110, v39
	v_mul_u32_u24_e32 v112, 0x90, v39
	v_lshl_or_b32 v94, s4, 11, v45
	v_add_u32_e32 v119, v42, v43
	v_add_u32_e32 v120, v107, v52
	v_add_u32_e32 v121, v44, v112
	v_mov_b64_e32 v[36:37], 0
	v_mov_b64_e32 v[38:39], 0
	v_mov_b64_e32 v[40:41], 0
	v_mov_b64_e32 v[42:43], 0
	v_mov_b64_e32 v[44:45], 0
	v_mov_b64_e32 v[46:47], 0
	v_mov_b64_e32 v[48:49], 0
	v_mov_b64_e32 v[50:51], 0
	v_mov_b64_e32 v[52:53], 0
	v_mov_b64_e32 v[54:55], 0
	v_mov_b64_e32 v[56:57], 0
	v_mov_b64_e32 v[58:59], 0
	v_mov_b64_e32 v[60:61], 0
	v_mov_b64_e32 v[62:63], 0
	v_mov_b64_e32 v[64:65], 0
	v_mov_b64_e32 v[66:67], 0
	s_mov_b32 s64, 0
	s_mov_b32 s65, 0
	s_mov_b32 s66, 0
	s_mov_b32 s67, 0xd000
	s_mul_i32 s68, s30, 0x2400
	s_sub_i32 s68, 168960, s68
	s_waitcnt vmcnt(0)
	s_barrier
